# P1 K-loop: one static s_setprio raise for the trailing wave half instead of per-MFMA-segment priority toggles (on top of v73)
# baseline (speedup 1.0000x reference)
; #define PG8_WAIT_V(n) asm volatile("s_waitcnt vmcnt(" #n ")" ::: "memory")
; #define PG8_BAR __builtin_amdgcn_s_barrier()
; template <class Epi, class Sched, bool ALIGN_EPI = false, bool SP2 = false>
; __device__ __forceinline__ void gemm_phase(PG8_LAS unsigned char* lds, const Gemm g, const Sched& S, const Epi& E) {
;     ...
;     PG8_WAIT_V(0);
;     if constexpr (!ALIGN_EPI) { if (wr == 0) PG8_BAR; }
;     PG8_BAR;
.LBB0_139:
	s_waitcnt vmcnt(0)
	s_mov_b64 s[58:59], s[20:21]
	s_mov_b64 s[62:63], s[22:23]
	s_setprio 0
	s_barrier

; #define PG8_STAGE(bufoff, gbase, voff) do { _Pragma("unroll") for (int _i = 0; _i < 2; ++_i) \
;         __builtin_amdgcn_global_load_lds((const unsigned*)((const char*)(gbase) + (voff)[_i]), (PG8_LAS unsigned*)(lds + (bufoff) + ldsw + _i * 8192), 16, 0, 0); } while (0)
; #define PG8_BAR __builtin_amdgcn_s_barrier()
; template <class Epi, class Sched, bool ALIGN_EPI = false, bool SP2 = false>
; __device__ __forceinline__ void gemm_phase(PG8_LAS unsigned char* lds, const Gemm g, const Sched& S, const Epi& E) {
;     ...
;     for (int i = 0; i < 2; ++i) { int R, C; stage_rc(tid * 16 + i * 8192, R, C); const int Rb = Epi::PERM ? ((R & ~31) + perm32(R & 31)) : R;
;         voffA[i] = (unsigned)(R * K + C) * 2u; voffB[i] = (unsigned)(Rb * K + C) * 2u; }
;     ...
;         PG8_STAGE(PG8_SB(0, 0), cB, voffB); PG8_STAGE(PG8_SB(0, 1), cB + hstep, voffB); PG8_STAGE(PG8_SA(0, 0), cA, voffA); PG8_STAGE(PG8_SA(0, 1), cA + hstep, voffA);
;         if (wr == 1) PG8_BAR;
.LBB0_238:
	s_and_b64 vcc, exec, s[0:1]
	s_cbranch_vccz .LBB0_140
	v_readlane_b32 s0, v247, 35
	s_waitcnt vmcnt(0)
	v_mov_b32_e32 v3, v0
	v_readlane_b32 s1, v247, 36
	s_andn2_b64 vcc, exec, s[0:1]
	v_readfirstlane_b32 s0, v3
	s_cbranch_vccnz .LBB0_140
	v_lshlrev_b32_e32 v5, 4, v3
	v_add_u32_e32 v4, 0x2000, v5
	v_ashrrev_i32_e32 v2, 31, v4
	v_lshrrev_b32_e32 v2, 22, v2
	v_add_u32_e32 v2, v4, v2
	v_ashrrev_i32_e32 v2, 10, v2
	s_waitcnt vmcnt(2)
	v_mul_i32_i24_e32 v6, 0x400, v2
	v_sub_u32_e32 v4, v4, v6
	v_lshrrev_b32_e32 v6, 4, v4
	v_bitop3_b32 v6, v6, v4, 32 bitop3:0x6c
	v_ashrrev_i32_e32 v4, 31, v6
	v_lshrrev_b32_e32 v4, 26, v4
	v_add_u32_e32 v7, v6, v4
	v_lshlrev_b32_e32 v8, 3, v2
	v_ashrrev_i32_e32 v4, 6, v7
	v_and_b32_e32 v8, -16, v8
	v_add_u32_e32 v8, v4, v8
	v_and_b32_e32 v9, 3, v4
	s_mov_b32 s2, 0x1fffe0
	s_waitcnt vmcnt(1)
	v_lshrrev_b32_e32 v10, 2, v8
	v_lshlrev_b32_e32 v11, 1, v8
	v_and_b32_e32 v7, 0xc0, v7
	v_and_or_b32 v9, v8, s2, v9
	v_and_b32_e32 v10, 4, v10
	v_and_b32_e32 v11, 24, v11
	v_sub_u32_e32 v6, v6, v7
	v_or3_b32 v9, v9, v10, v11
	v_lshlrev_b32_e32 v10, 5, v2
	v_ashrrev_i16_sdwa v6, v155, sext(v6) dst_sel:DWORD dst_unused:UNUSED_PAD src0_sel:DWORD src1_sel:BYTE_0
	v_and_b32_e32 v10, 32, v10
	v_bfe_i32 v6, v6, 0, 16
	v_add_lshl_u32 v7, v10, v6, 1
	v_lshl_add_u32 v142, v9, 11, v7
	v_lshl_add_u32 v144, v8, 11, v7
	v_bfe_i32 v7, v3, 27, 1
	v_lshrrev_b32_e32 v7, 22, v7
	v_add_u32_e32 v7, v5, v7
	v_and_b32_e32 v7, 0xfffffc00, v7
	v_sub_u32_e32 v7, v5, v7
	v_lshrrev_b32_e32 v8, 4, v7
	v_bitop3_b32 v9, v8, v7, 32 bitop3:0x6c
	v_ashrrev_i32_e32 v8, 31, v3
	v_lshrrev_b32_e32 v8, 26, v8
	v_ashrrev_i32_e32 v7, 31, v9
	v_add_u32_e32 v8, v3, v8
	v_lshrrev_b32_e32 v7, 26, v7
	v_ashrrev_i32_e32 v8, 6, v8
	v_add_u32_e32 v10, v9, v7
	v_lshlrev_b32_e32 v11, 3, v8
	v_ashrrev_i32_e32 v7, 6, v10
	v_and_b32_e32 v11, -16, v11
	v_add_u32_e32 v11, v7, v11
	v_and_b32_e32 v12, 3, v7
	v_lshrrev_b32_e32 v13, 2, v11
	s_waitcnt vmcnt(0)
	v_lshlrev_b32_e32 v14, 1, v11
	v_and_b32_e32 v10, 0xc0, v10
	v_and_or_b32 v12, v11, s2, v12
	v_and_b32_e32 v13, 4, v13
	v_and_b32_e32 v14, 24, v14
	v_sub_u32_e32 v9, v9, v10
	s_ashr_i32 s1, s0, 6
	v_or3_b32 v12, v12, v13, v14
	v_lshlrev_b32_e32 v13, 5, v8
	v_ashrrev_i16_sdwa v9, v155, sext(v9) dst_sel:DWORD dst_unused:UNUSED_PAD src0_sel:DWORD src1_sel:BYTE_0
	s_lshl_b32 s50, s1, 10
	v_and_b32_e32 v13, 32, v13
	v_bfe_i32 v9, v9, 0, 16
	v_add_lshl_u32 v10, v13, v9, 1
	s_add_i32 s11, s50, 0
	v_lshl_add_u32 v130, v12, 11, v10
	s_add_i32 m0, s11, 0x10000
	v_readlane_b32 s4, v247, 39
	global_load_lds_dwordx4 v130, s[58:59]
	s_add_i32 m0, s11, 0x12000
	v_readlane_b32 s5, v247, 40
	global_load_lds_dwordx4 v142, s[58:59]
	s_add_i32 m0, s11, 0x14000
	v_lshl_add_u32 v146, v11, 11, v10
	s_add_i32 s30, s11, 0x2000
	s_nop 0
	global_load_lds_dwordx4 v130, s[4:5]
	s_add_i32 m0, s11, 0x16000
	s_add_i32 s31, s11, 0x4000
	global_load_lds_dwordx4 v142, s[4:5]
	s_mov_b32 m0, s11
	v_readlane_b32 s4, v247, 41
	global_load_lds_dwordx4 v146, s[62:63]
	s_mov_b32 m0, s30
	v_readlane_b32 s5, v247, 42
	global_load_lds_dwordx4 v144, s[62:63]
	s_mov_b32 m0, s31
	s_add_i32 s86, s11, 0x6000
	s_ashr_i32 s2, s0, 8
	s_nop 0
	global_load_lds_dwordx4 v146, s[4:5]
	s_mov_b32 m0, s86
	s_cmp_eq_u32 s2, 1
	global_load_lds_dwordx4 v144, s[4:5]
	s_cselect_b64 s[4:5], -1, 0
	s_cmp_lg_u32 s2, 1
	s_cbranch_scc1 .LBB0_242
	s_setprio 1
	s_barrier

; #define PG8_STAGE(bufoff, gbase, voff) do { _Pragma("unroll") for (int _i = 0; _i < 2; ++_i) \
;         __builtin_amdgcn_global_load_lds((const unsigned*)((const char*)(gbase) + (voff)[_i]), (PG8_LAS unsigned*)(lds + (bufoff) + ldsw + _i * 8192), 16, 0, 0); } while (0)
; #define PG8_LDA(dst, b, h) do { _Pragma("unroll") for (int m = 0; m < 4; ++m) _Pragma("unroll") for (int k = 0; k < 2; ++k) dst[m][k] = *(const PG8_LAS bf16x8*)(lds + PG8_SA(b, h) + aoff + m * 2048 + k * 1024); } while (0)
; #define PG8_LDB(dst, b, h) do { _Pragma("unroll") for (int n = 0; n < 2; ++n) _Pragma("unroll") for (int k = 0; k < 2; ++k) dst[n][k] = *(const PG8_LAS bf16x8*)(lds + PG8_SB(b, h) + boff + n * 2048 + k * 1024); } while (0)
; #define PG8_MMA(ai, bj, At, Bt) do { __builtin_amdgcn_s_setprio(1); _Pragma("unroll") for (int m = 0; m < 4; ++m) _Pragma("unroll") for (int n = 0; n < 2; ++n) _Pragma("unroll") for (int k = 0; k < 2; ++k) \
;         acc[ai][bj][m][n] = __builtin_amdgcn_mfma_f32_16x16x32_bf16(Bt[n][k], At[m][k], acc[ai][bj][m][n], 0, 0, 0); __builtin_amdgcn_s_setprio(0); } while (0)
; #define PG8_WAIT_V(n) asm volatile("s_waitcnt vmcnt(" #n ")" ::: "memory")
; #define PG8_WAIT_L(n) asm volatile("s_waitcnt lgkmcnt(" #n ")" ::: "memory")
; #define PG8_BAR __builtin_amdgcn_s_barrier()
; #define PG8_SCHED __builtin_amdgcn_sched_barrier(0)
; template <class Epi, class Sched, bool ALIGN_EPI = false, bool SP2 = false>
; __device__ __forceinline__ void gemm_phase(PG8_LAS unsigned char* lds, const Gemm g, const Sched& S, const Epi& E) {
;     ...
;             PG8_LDB(B0, 0, 0); PG8_LDB(B1, 0, 1); PG8_SCHED; PG8_LDA(At, 0, 0); PG8_STAGE(PG8_SA(1, 1), a1 + hstep, voffA);
;             PG8_WAIT_V(8); PG8_WAIT_L(0); PG8_BAR; PG8_MMA(0, 0, At, B0); PG8_MMA(0, 1, At, B1); PG8_BAR; PG8_SCHED;
;             PG8_LDA(At, 0, 1); PG8_STAGE(PG8_SB(0, 0), b2, voffB); PG8_STAGE(PG8_SB(0, 1), b2 + hstep, voffB); PG8_STAGE(PG8_SA(0, 0), a2, voffA);
;             PG8_WAIT_V(8); PG8_WAIT_L(0); PG8_BAR; PG8_MMA(1, 0, At, B0); PG8_MMA(1, 1, At, B1); PG8_BAR; PG8_SCHED;
.LBB0_252:
	s_add_u32 s12, s56, 0xfffc0080
	s_addc_u32 s13, s57, -1
	s_add_i32 s14, 0, 0x10000
	s_cmp_eq_u32 s10, 12
	s_cselect_b32 s67, s45, s13
	s_cselect_b32 s66, s61, s12
	v_add_u32_e32 v152, s14, v133
	s_cselect_b32 s59, s53, s2
	s_cselect_b32 s58, vcc_lo, vcc_hi
	s_add_i32 s15, 0, 0x14000
	ds_read_b128 v[162:165], v152
	ds_read_b128 v[166:169], v152 offset:1024
	ds_read_b128 v[170:173], v152 offset:2048
	ds_read_b128 v[174:177], v152 offset:3072
	v_add_u32_e32 v152, s15, v133
	ds_read_b128 v[178:181], v152
	ds_read_b128 v[182:185], v152 offset:1024
	ds_read_b128 v[186:189], v152 offset:2048
	ds_read_b128 v[190:193], v152 offset:3072
	v_lshl_add_u64 v[152:153], s[56:57], 0, v[148:149]
	s_add_i32 m0, s11, 0xc000
	ds_read_b128 v[194:197], v158
	ds_read_b128 v[198:201], v158 offset:1024
	ds_read_b128 v[202:205], v158 offset:2048
	ds_read_b128 v[206:209], v158 offset:3072
	ds_read_b128 v[210:213], v158 offset:4096
	ds_read_b128 v[214:217], v158 offset:5120
	ds_read_b128 v[218:221], v158 offset:6144
	ds_read_b128 v[222:225], v158 offset:7168
	global_load_lds_dwordx4 v[152:153], off
	v_lshl_add_u64 v[152:153], s[56:57], 0, v[150:151]
	s_add_i32 m0, s11, 0xe000
	s_nop 0
	global_load_lds_dwordx4 v[152:153], off
	s_waitcnt vmcnt(8)
	s_waitcnt lgkmcnt(0)
	s_barrier
	s_waitcnt lgkmcnt(0)
	v_mfma_f32_16x16x32_bf16 v[126:129], v[162:165], v[194:197], v[126:129]
	v_mfma_f32_16x16x32_bf16 v[122:125], v[170:173], v[194:197], v[122:125]
	v_mfma_f32_16x16x32_bf16 v[114:117], v[162:165], v[202:205], v[114:117]
	v_mfma_f32_16x16x32_bf16 v[106:109], v[170:173], v[202:205], v[106:109]
	v_mfma_f32_16x16x32_bf16 v[98:101], v[162:165], v[210:213], v[98:101]
	v_mfma_f32_16x16x32_bf16 v[90:93], v[170:173], v[210:213], v[90:93]
	v_mfma_f32_16x16x32_bf16 v[82:85], v[162:165], v[218:221], v[82:85]
	v_mfma_f32_16x16x32_bf16 v[74:77], v[170:173], v[218:221], v[74:77]
	v_mfma_f32_16x16x32_bf16 v[126:129], v[166:169], v[198:201], v[126:129]
	v_mfma_f32_16x16x32_bf16 v[122:125], v[174:177], v[198:201], v[122:125]
	v_mfma_f32_16x16x32_bf16 v[114:117], v[166:169], v[206:209], v[114:117]
	v_mfma_f32_16x16x32_bf16 v[106:109], v[174:177], v[206:209], v[106:109]
	v_mfma_f32_16x16x32_bf16 v[98:101], v[166:169], v[214:217], v[98:101]
	v_mfma_f32_16x16x32_bf16 v[90:93], v[174:177], v[214:217], v[90:93]
	v_mfma_f32_16x16x32_bf16 v[82:85], v[166:169], v[222:225], v[82:85]
	v_mfma_f32_16x16x32_bf16 v[74:77], v[174:177], v[222:225], v[74:77]
	v_mfma_f32_16x16x32_bf16 v[118:121], v[178:181], v[194:197], v[118:121]
	v_mfma_f32_16x16x32_bf16 v[110:113], v[186:189], v[194:197], v[110:113]
	v_mfma_f32_16x16x32_bf16 v[102:105], v[178:181], v[202:205], v[102:105]
	v_mfma_f32_16x16x32_bf16 v[94:97], v[186:189], v[202:205], v[94:97]
	v_mfma_f32_16x16x32_bf16 v[86:89], v[178:181], v[210:213], v[86:89]
	v_mfma_f32_16x16x32_bf16 v[78:81], v[186:189], v[210:213], v[78:81]
	v_mfma_f32_16x16x32_bf16 v[70:73], v[178:181], v[218:221], v[70:73]
	v_mfma_f32_16x16x32_bf16 v[66:69], v[186:189], v[218:221], v[66:69]
	v_mfma_f32_16x16x32_bf16 v[118:121], v[182:185], v[198:201], v[118:121]
	v_mfma_f32_16x16x32_bf16 v[110:113], v[190:193], v[198:201], v[110:113]
	v_mfma_f32_16x16x32_bf16 v[102:105], v[182:185], v[206:209], v[102:105]
	v_mfma_f32_16x16x32_bf16 v[94:97], v[190:193], v[206:209], v[94:97]
	v_mfma_f32_16x16x32_bf16 v[86:89], v[182:185], v[214:217], v[86:89]
	v_mfma_f32_16x16x32_bf16 v[78:81], v[190:193], v[214:217], v[78:81]
	v_mfma_f32_16x16x32_bf16 v[70:73], v[182:185], v[222:225], v[70:73]
	v_mfma_f32_16x16x32_bf16 v[66:69], v[190:193], v[222:225], v[66:69]
	s_barrier
	s_add_i32 s12, s14, s50
	v_lshl_add_u64 v[152:153], s[58:59], 0, v[130:131]
	s_mov_b32 m0, s12
	ds_read_b128 v[194:197], v158 offset:16384
	ds_read_b128 v[198:201], v158 offset:17408
	ds_read_b128 v[202:205], v158 offset:18432
	ds_read_b128 v[206:209], v158 offset:19456
	ds_read_b128 v[210:213], v158 offset:20480
	ds_read_b128 v[214:217], v158 offset:21504
	ds_read_b128 v[218:221], v158 offset:22528
	ds_read_b128 v[222:225], v158 offset:23552
	global_load_lds_dwordx4 v[152:153], off
	s_add_i32 m0, s12, 0x2000
	s_add_u32 s12, s58, 0x40000
	v_lshl_add_u64 v[226:227], s[58:59], 0, v[142:143]
	s_addc_u32 s13, s59, 0
	s_add_i32 s14, s15, s50
	global_load_lds_dwordx4 v[226:227], off
	v_lshl_add_u64 v[228:229], s[12:13], 0, v[130:131]
	s_mov_b32 m0, s14
	v_lshl_add_u64 v[230:231], s[66:67], 0, v[144:145]
	global_load_lds_dwordx4 v[228:229], off
	v_lshl_add_u64 v[228:229], s[12:13], 0, v[142:143]
	s_add_i32 m0, s14, 0x2000
	s_nop 0
	global_load_lds_dwordx4 v[228:229], off
	v_lshl_add_u64 v[228:229], s[66:67], 0, v[146:147]
	s_mov_b32 m0, s11
	s_nop 0
	global_load_lds_dwordx4 v[228:229], off
	s_mov_b32 m0, s30
	s_nop 0
	global_load_lds_dwordx4 v[230:231], off
	s_waitcnt vmcnt(8)
	s_waitcnt lgkmcnt(0)
	s_barrier
; #define PG8_STAGE(bufoff, gbase, voff) do { _Pragma("unroll") for (int _i = 0; _i < 2; ++_i) \
;         __builtin_amdgcn_global_load_lds((const unsigned*)((const char*)(gbase) + (voff)[_i]), (PG8_LAS unsigned*)(lds + (bufoff) + ldsw + _i * 8192), 16, 0, 0); } while (0)
; #define PG8_LDA(dst, b, h) do { _Pragma("unroll") for (int m = 0; m < 4; ++m) _Pragma("unroll") for (int k = 0; k < 2; ++k) dst[m][k] = *(const PG8_LAS bf16x8*)(lds + PG8_SA(b, h) + aoff + m * 2048 + k * 1024); } while (0)
; #define PG8_LDB(dst, b, h) do { _Pragma("unroll") for (int n = 0; n < 2; ++n) _Pragma("unroll") for (int k = 0; k < 2; ++k) dst[n][k] = *(const PG8_LAS bf16x8*)(lds + PG8_SB(b, h) + boff + n * 2048 + k * 1024); } while (0)
; #define PG8_MMA(ai, bj, At, Bt) do { __builtin_amdgcn_s_setprio(1); _Pragma("unroll") for (int m = 0; m < 4; ++m) _Pragma("unroll") for (int n = 0; n < 2; ++n) _Pragma("unroll") for (int k = 0; k < 2; ++k) \
;         acc[ai][bj][m][n] = __builtin_amdgcn_mfma_f32_16x16x32_bf16(Bt[n][k], At[m][k], acc[ai][bj][m][n], 0, 0, 0); __builtin_amdgcn_s_setprio(0); } while (0)
; #define PG8_WAIT_V(n) asm volatile("s_waitcnt vmcnt(" #n ")" ::: "memory")
; #define PG8_WAIT_L(n) asm volatile("s_waitcnt lgkmcnt(" #n ")" ::: "memory")
; #define PG8_BAR __builtin_amdgcn_s_barrier()
; #define PG8_SCHED __builtin_amdgcn_sched_barrier(0)
; template <class Epi, class Sched, bool ALIGN_EPI = false, bool SP2 = false>
; __device__ __forceinline__ void gemm_phase(PG8_LAS unsigned char* lds, const Gemm g, const Sched& S, const Epi& E) {
;     ...
;             PG8_WAIT_V(8); PG8_WAIT_L(0); PG8_BAR; PG8_MMA(1, 0, At, B0); PG8_MMA(1, 1, At, B1); PG8_BAR; PG8_SCHED;
;             PG8_LDB(B0, 1, 0); PG8_LDB(B1, 1, 1); PG8_SCHED; PG8_LDA(At, 1, 0); PG8_STAGE(PG8_SA(0, 1), a2 + hstep, voffA);
;             PG8_WAIT_V(8); PG8_WAIT_L(0); PG8_BAR; PG8_MMA(0, 0, At, B0); PG8_MMA(0, 1, At, B1); PG8_BAR; PG8_SCHED;
	s_waitcnt lgkmcnt(0)
	v_mfma_f32_16x16x32_bf16 v[62:65], v[162:165], v[194:197], v[62:65]
	v_mfma_f32_16x16x32_bf16 v[58:61], v[170:173], v[194:197], v[58:61]
	v_mfma_f32_16x16x32_bf16 v[50:53], v[162:165], v[202:205], v[50:53]
	v_mfma_f32_16x16x32_bf16 v[42:45], v[170:173], v[202:205], v[42:45]
	v_mfma_f32_16x16x32_bf16 v[34:37], v[162:165], v[210:213], v[34:37]
	v_mfma_f32_16x16x32_bf16 v[26:29], v[170:173], v[210:213], v[26:29]
	v_mfma_f32_16x16x32_bf16 v[18:21], v[162:165], v[218:221], v[18:21]
	v_mfma_f32_16x16x32_bf16 v[10:13], v[170:173], v[218:221], v[10:13]
	v_mfma_f32_16x16x32_bf16 v[62:65], v[166:169], v[198:201], v[62:65]
	v_mfma_f32_16x16x32_bf16 v[58:61], v[174:177], v[198:201], v[58:61]
	v_mfma_f32_16x16x32_bf16 v[50:53], v[166:169], v[206:209], v[50:53]
	v_mfma_f32_16x16x32_bf16 v[42:45], v[174:177], v[206:209], v[42:45]
	v_mfma_f32_16x16x32_bf16 v[34:37], v[166:169], v[214:217], v[34:37]
	v_mfma_f32_16x16x32_bf16 v[26:29], v[174:177], v[214:217], v[26:29]
	v_mfma_f32_16x16x32_bf16 v[18:21], v[166:169], v[222:225], v[18:21]
	v_mfma_f32_16x16x32_bf16 v[10:13], v[174:177], v[222:225], v[10:13]
	v_mfma_f32_16x16x32_bf16 v[54:57], v[178:181], v[194:197], v[54:57]
	v_mfma_f32_16x16x32_bf16 v[46:49], v[186:189], v[194:197], v[46:49]
	v_mfma_f32_16x16x32_bf16 v[38:41], v[178:181], v[202:205], v[38:41]
	v_mfma_f32_16x16x32_bf16 v[30:33], v[186:189], v[202:205], v[30:33]
	v_mfma_f32_16x16x32_bf16 v[22:25], v[178:181], v[210:213], v[22:25]
	v_mfma_f32_16x16x32_bf16 v[14:17], v[186:189], v[210:213], v[14:17]
	v_mfma_f32_16x16x32_bf16 v[6:9], v[178:181], v[218:221], v[6:9]
	v_mfma_f32_16x16x32_bf16 v[2:5], v[186:189], v[218:221], v[2:5]
	v_mfma_f32_16x16x32_bf16 v[54:57], v[182:185], v[198:201], v[54:57]
	v_mfma_f32_16x16x32_bf16 v[46:49], v[190:193], v[198:201], v[46:49]
	v_mfma_f32_16x16x32_bf16 v[38:41], v[182:185], v[206:209], v[38:41]
	v_mfma_f32_16x16x32_bf16 v[30:33], v[190:193], v[206:209], v[30:33]
	v_mfma_f32_16x16x32_bf16 v[22:25], v[182:185], v[214:217], v[22:25]
	v_mfma_f32_16x16x32_bf16 v[14:17], v[190:193], v[214:217], v[14:17]
	v_mfma_f32_16x16x32_bf16 v[6:9], v[182:185], v[222:225], v[6:9]
	v_mfma_f32_16x16x32_bf16 v[2:5], v[190:193], v[222:225], v[2:5]
	s_barrier
	s_add_i32 s14, 0, 0x18000
	v_add_u32_e32 v161, s14, v133
	s_add_i32 s15, 0, 0x1c000
	ds_read_b128 v[162:165], v161
	ds_read_b128 v[166:169], v161 offset:1024
	ds_read_b128 v[170:173], v161 offset:2048
	ds_read_b128 v[174:177], v161 offset:3072
	v_add_u32_e32 v161, s15, v133
	ds_read_b128 v[178:181], v161
	ds_read_b128 v[182:185], v161 offset:1024
	ds_read_b128 v[186:189], v161 offset:2048
	ds_read_b128 v[190:193], v161 offset:3072
	s_add_u32 s12, s66, 0x40000
	s_addc_u32 s13, s67, 0
	s_mov_b32 m0, s31
	v_lshl_add_u64 v[232:233], s[12:13], 0, v[146:147]
	ds_read_b128 v[194:197], v158 offset:32768
	ds_read_b128 v[198:201], v158 offset:33792
	ds_read_b128 v[202:205], v158 offset:34816
	ds_read_b128 v[206:209], v158 offset:35840
	ds_read_b128 v[210:213], v158 offset:36864
	ds_read_b128 v[214:217], v158 offset:37888
	ds_read_b128 v[218:221], v158 offset:38912
	ds_read_b128 v[222:225], v158 offset:39936
	global_load_lds_dwordx4 v[232:233], off
	v_lshl_add_u64 v[232:233], s[12:13], 0, v[144:145]
	s_mov_b32 m0, s86
	s_nop 0
	global_load_lds_dwordx4 v[232:233], off
	s_waitcnt vmcnt(8)
	s_waitcnt lgkmcnt(0)
	s_barrier
	s_waitcnt lgkmcnt(0)
	v_mfma_f32_16x16x32_bf16 v[126:129], v[162:165], v[194:197], v[126:129]
	v_mfma_f32_16x16x32_bf16 v[122:125], v[170:173], v[194:197], v[122:125]
	v_mfma_f32_16x16x32_bf16 v[114:117], v[162:165], v[202:205], v[114:117]
	v_mfma_f32_16x16x32_bf16 v[106:109], v[170:173], v[202:205], v[106:109]
	v_mfma_f32_16x16x32_bf16 v[98:101], v[162:165], v[210:213], v[98:101]
	v_mfma_f32_16x16x32_bf16 v[90:93], v[170:173], v[210:213], v[90:93]
	v_mfma_f32_16x16x32_bf16 v[82:85], v[162:165], v[218:221], v[82:85]
	v_mfma_f32_16x16x32_bf16 v[74:77], v[170:173], v[218:221], v[74:77]
	v_mfma_f32_16x16x32_bf16 v[126:129], v[166:169], v[198:201], v[126:129]
	v_mfma_f32_16x16x32_bf16 v[122:125], v[174:177], v[198:201], v[122:125]
	v_mfma_f32_16x16x32_bf16 v[114:117], v[166:169], v[206:209], v[114:117]
	v_mfma_f32_16x16x32_bf16 v[106:109], v[174:177], v[206:209], v[106:109]
	v_mfma_f32_16x16x32_bf16 v[98:101], v[166:169], v[214:217], v[98:101]
	v_mfma_f32_16x16x32_bf16 v[90:93], v[174:177], v[214:217], v[90:93]
	v_mfma_f32_16x16x32_bf16 v[82:85], v[166:169], v[222:225], v[82:85]
	v_mfma_f32_16x16x32_bf16 v[74:77], v[174:177], v[222:225], v[74:77]
	v_mfma_f32_16x16x32_bf16 v[118:121], v[178:181], v[194:197], v[118:121]
	v_mfma_f32_16x16x32_bf16 v[110:113], v[186:189], v[194:197], v[110:113]
	v_mfma_f32_16x16x32_bf16 v[102:105], v[178:181], v[202:205], v[102:105]
	v_mfma_f32_16x16x32_bf16 v[94:97], v[186:189], v[202:205], v[94:97]
	v_mfma_f32_16x16x32_bf16 v[86:89], v[178:181], v[210:213], v[86:89]
	v_mfma_f32_16x16x32_bf16 v[78:81], v[186:189], v[210:213], v[78:81]
	v_mfma_f32_16x16x32_bf16 v[70:73], v[178:181], v[218:221], v[70:73]
	v_mfma_f32_16x16x32_bf16 v[66:69], v[186:189], v[218:221], v[66:69]
	v_mfma_f32_16x16x32_bf16 v[118:121], v[182:185], v[198:201], v[118:121]
	v_mfma_f32_16x16x32_bf16 v[110:113], v[190:193], v[198:201], v[110:113]
	v_mfma_f32_16x16x32_bf16 v[102:105], v[182:185], v[206:209], v[102:105]
	v_mfma_f32_16x16x32_bf16 v[94:97], v[190:193], v[206:209], v[94:97]
	v_mfma_f32_16x16x32_bf16 v[86:89], v[182:185], v[214:217], v[86:89]
	v_mfma_f32_16x16x32_bf16 v[78:81], v[190:193], v[214:217], v[78:81]
	v_mfma_f32_16x16x32_bf16 v[70:73], v[182:185], v[222:225], v[70:73]
	v_mfma_f32_16x16x32_bf16 v[66:69], v[190:193], v[222:225], v[66:69]
	s_barrier
; #define PG8_STAGE(bufoff, gbase, voff) do { _Pragma("unroll") for (int _i = 0; _i < 2; ++_i) \
;         __builtin_amdgcn_global_load_lds((const unsigned*)((const char*)(gbase) + (voff)[_i]), (PG8_LAS unsigned*)(lds + (bufoff) + ldsw + _i * 8192), 16, 0, 0); } while (0)
; #define PG8_LDA(dst, b, h) do { _Pragma("unroll") for (int m = 0; m < 4; ++m) _Pragma("unroll") for (int k = 0; k < 2; ++k) dst[m][k] = *(const PG8_LAS bf16x8*)(lds + PG8_SA(b, h) + aoff + m * 2048 + k * 1024); } while (0)
; #define PG8_MMA(ai, bj, At, Bt) do { __builtin_amdgcn_s_setprio(1); _Pragma("unroll") for (int m = 0; m < 4; ++m) _Pragma("unroll") for (int n = 0; n < 2; ++n) _Pragma("unroll") for (int k = 0; k < 2; ++k) \
;         acc[ai][bj][m][n] = __builtin_amdgcn_mfma_f32_16x16x32_bf16(Bt[n][k], At[m][k], acc[ai][bj][m][n], 0, 0, 0); __builtin_amdgcn_s_setprio(0); } while (0)
; #define PG8_WAIT_V(n) asm volatile("s_waitcnt vmcnt(" #n ")" ::: "memory")
; #define PG8_WAIT_L(n) asm volatile("s_waitcnt lgkmcnt(" #n ")" ::: "memory")
; #define PG8_BAR __builtin_amdgcn_s_barrier()
; #define PG8_SCHED __builtin_amdgcn_sched_barrier(0)
; template <class Epi, class Sched, bool ALIGN_EPI = false, bool SP2 = false>
; __device__ __forceinline__ void gemm_phase(PG8_LAS unsigned char* lds, const Gemm g, const Sched& S, const Epi& E) {
;     ...
;             PG8_LDA(At, 1, 1); PG8_STAGE(PG8_SB(1, 0), b3, voffB); PG8_STAGE(PG8_SB(1, 1), b3 + hstep, voffB); PG8_STAGE(PG8_SA(1, 0), a3, voffA);
;             PG8_WAIT_V(8); PG8_WAIT_L(0); PG8_BAR; PG8_MMA(1, 0, At, B0); PG8_MMA(1, 1, At, B1); PG8_BAR; PG8_SCHED;
;     ...
;         if constexpr (ALIGN_EPI) { if (wr == 0) PG8_BAR; }
	s_add_i32 s12, s14, s50
	v_lshl_add_u64 v[152:153], v[152:153], 0, s[46:47]
	s_mov_b32 m0, s12
	ds_read_b128 v[194:197], v158 offset:49152
	ds_read_b128 v[198:201], v158 offset:50176
	ds_read_b128 v[202:205], v158 offset:51200
	ds_read_b128 v[206:209], v158 offset:52224
	ds_read_b128 v[210:213], v158 offset:53248
	ds_read_b128 v[214:217], v158 offset:54272
	ds_read_b128 v[218:221], v158 offset:55296
	ds_read_b128 v[222:225], v158 offset:56320
	global_load_lds_dwordx4 v[152:153], off
	s_add_i32 m0, s12, 0x2000
	s_add_u32 s12, s58, 0x40080
	v_lshl_add_u64 v[152:153], v[226:227], 0, s[46:47]
	s_addc_u32 s13, s59, 0
	s_add_i32 s14, s15, s50
	global_load_lds_dwordx4 v[152:153], off
	v_lshl_add_u64 v[152:153], s[12:13], 0, v[130:131]
	s_mov_b32 m0, s14
	s_nop 0
	global_load_lds_dwordx4 v[152:153], off
	v_lshl_add_u64 v[152:153], s[12:13], 0, v[142:143]
	s_add_i32 m0, s14, 0x2000
	s_nop 0
	global_load_lds_dwordx4 v[152:153], off
	v_lshl_add_u64 v[152:153], v[228:229], 0, s[46:47]
	s_mov_b32 m0, s38
	s_nop 0
	global_load_lds_dwordx4 v[152:153], off
	v_lshl_add_u64 v[152:153], v[230:231], 0, s[46:47]
	s_mov_b32 m0, s39
	s_nop 0
	global_load_lds_dwordx4 v[152:153], off
	s_waitcnt vmcnt(8)
	s_waitcnt lgkmcnt(0)
	s_barrier
	s_waitcnt lgkmcnt(0)
	v_mfma_f32_16x16x32_bf16 v[62:65], v[162:165], v[194:197], v[62:65]
	v_mfma_f32_16x16x32_bf16 v[58:61], v[170:173], v[194:197], v[58:61]
	v_mfma_f32_16x16x32_bf16 v[50:53], v[162:165], v[202:205], v[50:53]
	v_mfma_f32_16x16x32_bf16 v[42:45], v[170:173], v[202:205], v[42:45]
	v_mfma_f32_16x16x32_bf16 v[34:37], v[162:165], v[210:213], v[34:37]
	v_mfma_f32_16x16x32_bf16 v[26:29], v[170:173], v[210:213], v[26:29]
	v_mfma_f32_16x16x32_bf16 v[18:21], v[162:165], v[218:221], v[18:21]
	v_mfma_f32_16x16x32_bf16 v[10:13], v[170:173], v[218:221], v[10:13]
	v_mfma_f32_16x16x32_bf16 v[62:65], v[166:169], v[198:201], v[62:65]
	v_mfma_f32_16x16x32_bf16 v[58:61], v[174:177], v[198:201], v[58:61]
	v_mfma_f32_16x16x32_bf16 v[50:53], v[166:169], v[206:209], v[50:53]
	v_mfma_f32_16x16x32_bf16 v[42:45], v[174:177], v[206:209], v[42:45]
	v_mfma_f32_16x16x32_bf16 v[34:37], v[166:169], v[214:217], v[34:37]
	v_mfma_f32_16x16x32_bf16 v[26:29], v[174:177], v[214:217], v[26:29]
	v_mfma_f32_16x16x32_bf16 v[18:21], v[166:169], v[222:225], v[18:21]
	v_mfma_f32_16x16x32_bf16 v[10:13], v[174:177], v[222:225], v[10:13]
	v_mfma_f32_16x16x32_bf16 v[54:57], v[178:181], v[194:197], v[54:57]
	v_mfma_f32_16x16x32_bf16 v[46:49], v[186:189], v[194:197], v[46:49]
	v_mfma_f32_16x16x32_bf16 v[38:41], v[178:181], v[202:205], v[38:41]
	v_mfma_f32_16x16x32_bf16 v[30:33], v[186:189], v[202:205], v[30:33]
	v_mfma_f32_16x16x32_bf16 v[22:25], v[178:181], v[210:213], v[22:25]
	v_mfma_f32_16x16x32_bf16 v[14:17], v[186:189], v[210:213], v[14:17]
	v_mfma_f32_16x16x32_bf16 v[6:9], v[178:181], v[218:221], v[6:9]
	v_mfma_f32_16x16x32_bf16 v[2:5], v[186:189], v[218:221], v[2:5]
	v_mfma_f32_16x16x32_bf16 v[54:57], v[182:185], v[198:201], v[54:57]
	v_mfma_f32_16x16x32_bf16 v[46:49], v[190:193], v[198:201], v[46:49]
	v_mfma_f32_16x16x32_bf16 v[38:41], v[182:185], v[206:209], v[38:41]
	v_mfma_f32_16x16x32_bf16 v[30:33], v[190:193], v[206:209], v[30:33]
	v_mfma_f32_16x16x32_bf16 v[22:25], v[182:185], v[214:217], v[22:25]
	v_mfma_f32_16x16x32_bf16 v[14:17], v[190:193], v[214:217], v[14:17]
	v_mfma_f32_16x16x32_bf16 v[6:9], v[182:185], v[222:225], v[6:9]
	v_mfma_f32_16x16x32_bf16 v[2:5], v[190:193], v[222:225], v[2:5]
	s_barrier
	s_add_i32 s10, s10, 2
	s_add_u32 s56, s56, 0x100
	s_addc_u32 s57, s57, 0
	s_add_u32 vcc_hi, vcc_hi, 0x100
	s_addc_u32 s2, s2, 0
	s_cmp_gt_u32 s10, 13
	s_cbranch_scc0 .LBB0_252
	s_and_b64 vcc, exec, s[48:49]
	s_cbranch_vccz .LBB0_255
	s_barrier
